# NSA selected branch: in-range-bias tiles rewritten in place (no accumulator copies, batched bias lookups, packed sub/sum)
# speedup vs baseline: 1.0050x; 1.0050x over previous
.LBB0_430:
	s_andn2_b64 vcc, exec, s[6:7]
	s_cbranch_vccnz .LBB0_438
	v_cmp_ne_u32_e32 vcc, 0, v139
	s_cbranch_vccz .Lsel_fast
	v_add_u32_e32 v54, s13, v196
	v_cmp_ne_u32_e32 vcc, 0, v0
	v_sub_u32_e32 v0, s14, v140
	v_add_u32_e32 v62, v54, v194
	v_add_u32_e32 v89, v54, v195
	v_lshl_add_u32 v0, v0, 2, v216
	s_cbranch_vccz .Lp1_skip0
	v_add_u32_e32 v63, 0xffc, v0
	ds_read_b128 v[54:57], v62 offset:16384
	ds_read_b128 v[58:61], v62 offset:18432
	ds_read_b128 v[64:67], v62 offset:20480
	ds_read_b128 v[68:71], v89 offset:16384
	ds_read_b128 v[72:75], v62 offset:22528
	ds_read2_b32 v[90:91], v63 offset1:1
	ds_read2_b32 v[92:93], v63 offset0:2 offset1:3
	ds_read2_b32 v[94:95], v63 offset0:16 offset1:17
	ds_read2_b32 v[96:97], v63 offset0:18 offset1:19
	ds_read2_b32 v[98:99], v63 offset0:32 offset1:33
	ds_read2_b32 v[100:101], v63 offset0:34 offset1:35
	ds_read2_b32 v[154:155], v63 offset0:48 offset1:49
	ds_read2_b32 v[156:157], v63 offset0:50 offset1:51
	s_waitcnt lgkmcnt(8)
	v_mfma_f32_16x16x32_bf16 v[54:57], v[54:57], v[2:5], 0
	v_mfma_f32_16x16x32_bf16 v[58:61], v[58:61], v[2:5], 0
	v_mfma_f32_16x16x32_bf16 v[54:57], v[68:71], v[6:9], v[54:57]
	ds_read_b128 v[68:71], v89 offset:18432
	ds_read_b128 v[76:79], v89 offset:20480
	v_mfma_f32_16x16x32_bf16 v[64:67], v[64:67], v[2:5], 0
	v_mfma_f32_16x16x32_bf16 v[84:87], v[72:75], v[2:5], 0
	s_waitcnt lgkmcnt(0)
	v_mfma_f32_16x16x32_bf16 v[58:61], v[68:71], v[6:9], v[58:61]
	ds_read_b128 v[68:71], v89 offset:22528
	v_mfma_f32_16x16x32_bf16 v[64:67], v[76:79], v[6:9], v[64:67]
	s_waitcnt lgkmcnt(0)
	v_mfma_f32_16x16x32_bf16 v[84:87], v[68:71], v[6:9], v[84:87]
	v_pk_fma_f32 v[54:55], v[54:55], s[36:37], v[90:91] op_sel_hi:[1,0,1]
	v_pk_fma_f32 v[56:57], v[56:57], s[36:37], v[92:93] op_sel_hi:[1,0,1]
	s_nop 1
	v_pk_fma_f32 v[58:59], v[58:59], s[36:37], v[94:95] op_sel_hi:[1,0,1]
	v_pk_fma_f32 v[60:61], v[60:61], s[36:37], v[96:97] op_sel_hi:[1,0,1]
	v_pk_fma_f32 v[64:65], v[64:65], s[36:37], v[98:99] op_sel_hi:[1,0,1]
	v_pk_fma_f32 v[66:67], v[66:67], s[36:37], v[100:101] op_sel_hi:[1,0,1]
	v_pk_fma_f32 v[84:85], v[84:85], s[36:37], v[154:155] op_sel_hi:[1,0,1]
	v_pk_fma_f32 v[86:87], v[86:87], s[36:37], v[156:157] op_sel_hi:[1,0,1]
	v_max3_f32 v63, v54, v55, v56
	v_max3_f32 v63, v63, v57, v58
	v_max3_f32 v63, v63, v59, v60
	v_max3_f32 v63, v63, v61, v64
	v_max3_f32 v63, v63, v65, v66
	v_max3_f32 v63, v63, v67, v84
	v_max3_f32 v63, v63, v85, v86
	v_max3_f32 v63, v63, v87, s29
	ds_bpermute_b32 v68, v119, v63
	s_waitcnt lgkmcnt(0)
	v_max_f32_e32 v63, v63, v68
	ds_bpermute_b32 v68, v137, v63
	s_waitcnt lgkmcnt(0)
	v_max_f32_e32 v63, v63, v68
	v_cndmask_b32_e64 v63, v148, v63, s[44:45]
	v_max_f32_e32 v68, v160, v63
	v_sub_f32_e32 v69, v160, v68
	v_exp_f32_e32 v70, v69
	v_cndmask_b32_e64 v82, v209, v68, s[44:45]
	v_mov_b32_e32 v160, v68
	v_pk_mul_f32 v[36:37], v[36:37], v[70:71] op_sel_hi:[1,0]
	v_pk_mul_f32 v[34:35], v[34:35], v[70:71] op_sel_hi:[1,0]
	v_pk_mul_f32 v[48:49], v[48:49], v[70:71] op_sel_hi:[1,0]
	v_pk_mul_f32 v[46:47], v[46:47], v[70:71] op_sel_hi:[1,0]
	v_pk_mul_f32 v[44:45], v[44:45], v[70:71] op_sel_hi:[1,0]
	v_pk_mul_f32 v[42:43], v[42:43], v[70:71] op_sel_hi:[1,0]
	v_pk_mul_f32 v[52:53], v[52:53], v[70:71] op_sel_hi:[1,0]
	v_pk_mul_f32 v[50:51], v[50:51], v[70:71] op_sel_hi:[1,0]
	v_pk_add_f32 v[54:55], v[54:55], v[82:83] op_sel_hi:[1,0] neg_lo:[0,1] neg_hi:[0,1]
	v_pk_add_f32 v[56:57], v[56:57], v[82:83] op_sel_hi:[1,0] neg_lo:[0,1] neg_hi:[0,1]
	v_pk_add_f32 v[58:59], v[58:59], v[82:83] op_sel_hi:[1,0] neg_lo:[0,1] neg_hi:[0,1]
	v_pk_add_f32 v[60:61], v[60:61], v[82:83] op_sel_hi:[1,0] neg_lo:[0,1] neg_hi:[0,1]
	v_pk_add_f32 v[64:65], v[64:65], v[82:83] op_sel_hi:[1,0] neg_lo:[0,1] neg_hi:[0,1]
	v_pk_add_f32 v[66:67], v[66:67], v[82:83] op_sel_hi:[1,0] neg_lo:[0,1] neg_hi:[0,1]
	v_pk_add_f32 v[84:85], v[84:85], v[82:83] op_sel_hi:[1,0] neg_lo:[0,1] neg_hi:[0,1]
	v_pk_add_f32 v[86:87], v[86:87], v[82:83] op_sel_hi:[1,0] neg_lo:[0,1] neg_hi:[0,1]
	v_exp_f32_e32 v54, v54
	v_exp_f32_e32 v55, v55
	v_exp_f32_e32 v56, v56
	v_exp_f32_e32 v57, v57
	v_exp_f32_e32 v58, v58
	v_exp_f32_e32 v59, v59
	v_exp_f32_e32 v60, v60
	v_exp_f32_e32 v61, v61
	v_exp_f32_e32 v64, v64
	v_exp_f32_e32 v65, v65
	v_exp_f32_e32 v66, v66
	v_exp_f32_e32 v67, v67
	v_exp_f32_e32 v84, v84
	v_exp_f32_e32 v85, v85
	v_exp_f32_e32 v86, v86
	v_exp_f32_e32 v87, v87
	s_nop 0
	v_pk_add_f32 v[72:73], v[54:55], v[56:57]
	v_pk_add_f32 v[74:75], v[58:59], v[60:61]
	v_pk_add_f32 v[76:77], v[64:65], v[66:67]
	v_pk_add_f32 v[78:79], v[84:85], v[86:87]
	v_pk_add_f32 v[72:73], v[72:73], v[74:75]
	v_pk_add_f32 v[76:77], v[76:77], v[78:79]
	s_nop 0
	v_pk_add_f32 v[72:73], v[72:73], v[76:77]
	s_nop 0
	v_add_f32_e32 v72, v72, v73
	v_fma_f32 v144, v144, v70, v72
	v_cvt_pk_bf16_f32 v61, v60, v61
	v_cvt_pk_bf16_f32 v60, v58, v59
	v_cvt_pk_bf16_f32 v59, v56, v57
	v_cvt_pk_bf16_f32 v58, v54, v55
	v_cvt_pk_bf16_f32 v54, v64, v65
	v_cvt_pk_bf16_f32 v55, v66, v67
	v_cvt_pk_bf16_f32 v56, v84, v85
	v_cvt_pk_bf16_f32 v57, v86, v87
	v_cndmask_b32_e64 v63, 0, 1, s[42:43]
	v_cmp_ne_u32_e32 vcc, 0, v63
	s_cbranch_vccz .LBB0_445
.Lp1_cb1:
	v_add_u32_e32 v88, 0xfec, v0
	ds_read_b128 v[64:67], v62 offset:16384
	ds_read_b128 v[68:71], v62 offset:18432
	ds_read_b128 v[72:75], v89 offset:16384
	ds_read_b128 v[76:79], v89 offset:18432
	ds_read2_b32 v[90:91], v88 offset1:1
	ds_read2_b32 v[92:93], v88 offset0:2 offset1:3
	ds_read2_b32 v[94:95], v88 offset0:16 offset1:17
	ds_read2_b32 v[96:97], v88 offset0:18 offset1:19
	ds_read2_b32 v[98:99], v88 offset0:32 offset1:33
	ds_read2_b32 v[100:101], v88 offset0:34 offset1:35
	ds_read2_b32 v[154:155], v88 offset0:48 offset1:49
	ds_read2_b32 v[156:157], v88 offset0:50 offset1:51
	s_waitcnt lgkmcnt(8)
	v_mfma_f32_16x16x32_bf16 v[64:67], v[64:67], v[10:13], 0
	v_mfma_f32_16x16x32_bf16 v[68:71], v[68:71], v[10:13], 0
	v_mfma_f32_16x16x32_bf16 v[64:67], v[72:75], v[14:17], v[64:67]
	ds_read_b128 v[72:75], v62 offset:20480
	v_mfma_f32_16x16x32_bf16 v[68:71], v[76:79], v[14:17], v[68:71]
	ds_read_b128 v[76:79], v89 offset:20480
	ds_read_b128 v[80:83], v62 offset:22528
	ds_read_b128 v[84:87], v89 offset:22528
	s_waitcnt lgkmcnt(0)
	v_mfma_f32_16x16x32_bf16 v[72:75], v[72:75], v[10:13], 0
	v_mfma_f32_16x16x32_bf16 v[80:83], v[80:83], v[10:13], 0
	v_mfma_f32_16x16x32_bf16 v[72:75], v[76:79], v[14:17], v[72:75]
	v_mfma_f32_16x16x32_bf16 v[80:83], v[84:87], v[14:17], v[80:83]
	v_pk_fma_f32 v[64:65], v[64:65], s[36:37], v[90:91] op_sel_hi:[1,0,1]
	v_pk_fma_f32 v[66:67], v[66:67], s[36:37], v[92:93] op_sel_hi:[1,0,1]
	v_pk_fma_f32 v[68:69], v[68:69], s[36:37], v[94:95] op_sel_hi:[1,0,1]
	v_pk_fma_f32 v[70:71], v[70:71], s[36:37], v[96:97] op_sel_hi:[1,0,1]
	s_nop 3
	v_pk_fma_f32 v[72:73], v[72:73], s[36:37], v[98:99] op_sel_hi:[1,0,1]
	v_pk_fma_f32 v[74:75], v[74:75], s[36:37], v[100:101] op_sel_hi:[1,0,1]
	v_pk_fma_f32 v[80:81], v[80:81], s[36:37], v[154:155] op_sel_hi:[1,0,1]
	v_pk_fma_f32 v[82:83], v[82:83], s[36:37], v[156:157] op_sel_hi:[1,0,1]
	v_max3_f32 v76, v64, v65, v66
	v_max3_f32 v76, v76, v67, v68
	v_max3_f32 v76, v76, v69, v70
	v_max3_f32 v76, v76, v71, v72
	v_max3_f32 v76, v76, v73, v74
	v_max3_f32 v76, v76, v75, v80
	v_max3_f32 v76, v76, v81, v82
	v_max3_f32 v76, v76, v83, s29
	ds_bpermute_b32 v77, v119, v76
	s_waitcnt lgkmcnt(0)
	v_max_f32_e32 v76, v76, v77
	ds_bpermute_b32 v77, v137, v76
	s_waitcnt lgkmcnt(0)
	v_max_f32_e32 v76, v76, v77
	v_cndmask_b32_e64 v76, v148, v76, s[42:43]
	v_max_f32_e32 v77, v161, v76
	v_sub_f32_e32 v0, v161, v77
	v_exp_f32_e32 v0, v0
	v_cndmask_b32_e64 v78, v209, v77, s[42:43]
	v_mov_b32_e32 v161, v77
	v_pk_mul_f32 v[32:33], v[32:33], v[0:1] op_sel_hi:[1,0]
	v_pk_mul_f32 v[30:31], v[30:31], v[0:1] op_sel_hi:[1,0]
	v_pk_mul_f32 v[28:29], v[28:29], v[0:1] op_sel_hi:[1,0]
	v_pk_mul_f32 v[26:27], v[26:27], v[0:1] op_sel_hi:[1,0]
	v_pk_mul_f32 v[24:25], v[24:25], v[0:1] op_sel_hi:[1,0]
	v_pk_mul_f32 v[22:23], v[22:23], v[0:1] op_sel_hi:[1,0]
	v_pk_mul_f32 v[20:21], v[20:21], v[0:1] op_sel_hi:[1,0]
	v_pk_mul_f32 v[18:19], v[18:19], v[0:1] op_sel_hi:[1,0]
	v_pk_add_f32 v[64:65], v[64:65], v[78:79] op_sel_hi:[1,0] neg_lo:[0,1] neg_hi:[0,1]
	v_pk_add_f32 v[66:67], v[66:67], v[78:79] op_sel_hi:[1,0] neg_lo:[0,1] neg_hi:[0,1]
	v_pk_add_f32 v[68:69], v[68:69], v[78:79] op_sel_hi:[1,0] neg_lo:[0,1] neg_hi:[0,1]
	v_pk_add_f32 v[70:71], v[70:71], v[78:79] op_sel_hi:[1,0] neg_lo:[0,1] neg_hi:[0,1]
	v_pk_add_f32 v[72:73], v[72:73], v[78:79] op_sel_hi:[1,0] neg_lo:[0,1] neg_hi:[0,1]
	v_pk_add_f32 v[74:75], v[74:75], v[78:79] op_sel_hi:[1,0] neg_lo:[0,1] neg_hi:[0,1]
	v_pk_add_f32 v[80:81], v[80:81], v[78:79] op_sel_hi:[1,0] neg_lo:[0,1] neg_hi:[0,1]
	v_pk_add_f32 v[82:83], v[82:83], v[78:79] op_sel_hi:[1,0] neg_lo:[0,1] neg_hi:[0,1]
	v_exp_f32_e32 v64, v64
	v_exp_f32_e32 v65, v65
	v_exp_f32_e32 v66, v66
	v_exp_f32_e32 v67, v67
	v_exp_f32_e32 v68, v68
	v_exp_f32_e32 v69, v69
	v_exp_f32_e32 v70, v70
	v_exp_f32_e32 v71, v71
	v_exp_f32_e32 v72, v72
	v_exp_f32_e32 v73, v73
	v_exp_f32_e32 v74, v74
	v_exp_f32_e32 v75, v75
	v_exp_f32_e32 v80, v80
	v_exp_f32_e32 v81, v81
	v_exp_f32_e32 v82, v82
	v_exp_f32_e32 v83, v83
	s_nop 0
	v_pk_add_f32 v[84:85], v[64:65], v[66:67]
	v_pk_add_f32 v[86:87], v[68:69], v[70:71]
	v_pk_add_f32 v[76:77], v[72:73], v[74:75]
	v_pk_add_f32 v[78:79], v[80:81], v[82:83]
	v_pk_add_f32 v[84:85], v[84:85], v[86:87]
	v_pk_add_f32 v[76:77], v[76:77], v[78:79]
	s_nop 0
	v_pk_add_f32 v[84:85], v[84:85], v[76:77]
	s_nop 0
	v_add_f32_e32 v84, v84, v85
	v_fma_f32 v145, v145, v0, v84
	v_cvt_pk_bf16_f32 v67, v66, v67
	v_cvt_pk_bf16_f32 v66, v64, v65
	v_cvt_pk_bf16_f32 v68, v68, v69
	v_cvt_pk_bf16_f32 v69, v70, v71
	v_cvt_pk_bf16_f32 v62, v72, v73
	v_cvt_pk_bf16_f32 v63, v74, v75
	v_cvt_pk_bf16_f32 v64, v80, v81
	v_cvt_pk_bf16_f32 v65, v82, v83
	s_branch .LBB0_446
.Lp1_skip0:
	v_mov_b32_e32 v54, 0
	v_mov_b32_e32 v55, v54
	v_mov_b32_e32 v56, v54
	v_mov_b32_e32 v57, v54
	v_mov_b32_e32 v58, v54
	v_mov_b32_e32 v59, v54
	v_mov_b32_e32 v60, v54
	v_mov_b32_e32 v61, v54
	v_cndmask_b32_e64 v63, 0, 1, s[42:43]
	v_cmp_ne_u32_e32 vcc, 0, v63
	s_cbranch_vccnz .Lp1_cb1
	s_branch .LBB0_445
